# SEAM(0) also routed through the shared grid-barrier copy
# baseline (speedup 1.0000x reference)
; __device__ __forceinline__ unsigned xb_ld(unsigned* p)              { return __hip_atomic_load(p, __ATOMIC_RELAXED, __HIP_MEMORY_SCOPE_AGENT); }
; __device__ __forceinline__ unsigned xb_add(unsigned* p, unsigned v) { return __hip_atomic_fetch_add(p, v, __ATOMIC_RELAXED, __HIP_MEMORY_SCOPE_AGENT); }
; #define XB_SPIN(cond, bar) do { unsigned _sp = 0; while (cond) { __builtin_amdgcn_s_sleep(1); \
;     if ((++_sp & 255u) == 0u) { if (xb_ld(&(bar)[XB_TMO])) break; if (_sp > XB_SPIN_CAP) { atomicAdd(&(bar)[XB_TMO], 1u); break; } } } } while (0)
; #define SEAM(k) do { if (IN(k) && IN((k) + 1)) xcd_barrier(bar); } while (0)
; __device__ __forceinline__ void xcd_barrier(const XcdBarrier& b) {
;     asm volatile("s_waitcnt vmcnt(0)" ::: "memory");
;     __syncthreads();
;     if (threadIdx.x == 0) {
;         unsigned* bar = b.bar;
;         __builtin_amdgcn_s_waitcnt(0);
;         unsigned nloc = b.st[0], nx = b.st[1];
;         if (nloc == 0u) { xcd_barrier_complete(bar, b.x, nloc, nx); b.st[0] = nloc; b.st[1] = nx; }
;         const unsigned old = xb_add(&bar[XB_XSUB(b.x)], 1u);
;         const unsigned gen = old / nloc;
;         if (old + 1u == (gen + 1u) * nloc) {
;             __builtin_amdgcn_fence(__ATOMIC_RELEASE, "agent");
;             asm volatile("s_waitcnt vmcnt(0)" ::: "memory");
;             const unsigned og = xb_add(&bar[XB_TOP], 1u);
;             const unsigned tg = og / nx;
;             if (og + 1u == (tg + 1u) * nx) xb_add(&bar[XB_TOPGEN], 1u);
;             else XB_SPIN(xb_ld(&bar[XB_TOPGEN]) == tg, bar);
;             __builtin_amdgcn_fence(__ATOMIC_ACQUIRE, "agent");
;             xb_add(&bar[XB_XGEN(b.x)], 1u);
;             asm volatile("s_waitcnt vmcnt(0)" ::: "memory");
;         } else {
;             XB_SPIN(xb_ld(&bar[XB_XGEN(b.x)]) == gen, bar);
;             __builtin_amdgcn_fence(__ATOMIC_ACQUIRE, "agent");
;             asm volatile("s_waitcnt vmcnt(0)" ::: "memory");
;         }
;     }
;     __syncthreads();
; }
; __global__ void __launch_bounds__(512, 2) mk_fwd(Args args) {
;     ...
;     SEAM(0);
.LBB0_14:
	s_cmp_gt_i32 s69, 1
	s_cselect_b64 s[4:5], -1, 0
	s_and_b64 s[0:1], s[6:7], s[4:5]
	s_andn2_b64 vcc, exec, s[0:1]
	s_cbranch_vccnz .LBB0_79
	s_waitcnt vmcnt(0)
	s_barrier
	s_and_saveexec_b64 s[6:7], s[92:93]
	s_cbranch_execz .LBB0_78
	s_mov_b32 s99, 7
	s_branch .Lseam_shared

; #define LAS __attribute__((address_space(3)))
; __device__ __forceinline__ void xcd_barrier(const XcdBarrier& b) {
;     ...
;     __syncthreads();
; }
; __global__ void __launch_bounds__(512, 2) mk_fwd(Args args) {
;     ...
;     if (tid < 16) ((LAS unsigned*)(lds + LDS_MISC))[tid] = 0u;
;     __syncthreads();
;     XcdBarrier bar = xcd_barrier_post((unsigned*)ws, (volatile LAS unsigned*)(lds + LDS_MISC));
.LBB0_36:
	s_or_b64 exec, exec, s[4:5]
	s_barrier
	s_load_dwordx8 s[60:67], s[0:1], 0x40
	v_cmp_gt_u32_e32 vcc, 16, v200
	s_and_saveexec_b64 s[4:5], vcc
	s_cbranch_execnz .LBB0_2
	s_branch .LBB0_3
.LBB0_78:
	s_or_b64 exec, exec, s[6:7]
	s_waitcnt lgkmcnt(0)
	s_barrier

; __device__ __forceinline__ unsigned xb_ld(unsigned* p)              { return __hip_atomic_load(p, __ATOMIC_RELAXED, __HIP_MEMORY_SCOPE_AGENT); }
; __device__ __forceinline__ unsigned xb_add(unsigned* p, unsigned v) { return __hip_atomic_fetch_add(p, v, __ATOMIC_RELAXED, __HIP_MEMORY_SCOPE_AGENT); }
; #define XB_SPIN(cond, bar) do { unsigned _sp = 0; while (cond) { __builtin_amdgcn_s_sleep(1); \
;     if ((++_sp & 255u) == 0u) { if (xb_ld(&(bar)[XB_TMO])) break; if (_sp > XB_SPIN_CAP) { atomicAdd(&(bar)[XB_TMO], 1u); break; } } } } while (0)
; __device__ __forceinline__ void xcd_barrier(const XcdBarrier& b) {
;     asm volatile("s_waitcnt vmcnt(0)" ::: "memory");
;     __syncthreads();
;     if (threadIdx.x == 0) {
;         unsigned* bar = b.bar;
;         __builtin_amdgcn_s_waitcnt(0);
;         unsigned nloc = b.st[0], nx = b.st[1];
;         if (nloc == 0u) { xcd_barrier_complete(bar, b.x, nloc, nx); b.st[0] = nloc; b.st[1] = nx; }
;         const unsigned old = xb_add(&bar[XB_XSUB(b.x)], 1u);
;         const unsigned gen = old / nloc;
;         if (old + 1u == (gen + 1u) * nloc) {
;             __builtin_amdgcn_fence(__ATOMIC_RELEASE, "agent");
;             asm volatile("s_waitcnt vmcnt(0)" ::: "memory");
;             const unsigned og = xb_add(&bar[XB_TOP], 1u);
;             const unsigned tg = og / nx;
;             if (og + 1u == (tg + 1u) * nx) xb_add(&bar[XB_TOPGEN], 1u);
;             else XB_SPIN(xb_ld(&bar[XB_TOPGEN]) == tg, bar);
;             __builtin_amdgcn_fence(__ATOMIC_ACQUIRE, "agent");
;             xb_add(&bar[XB_XGEN(b.x)], 1u);
;             asm volatile("s_waitcnt vmcnt(0)" ::: "memory");
;         } else {
;             XB_SPIN(xb_ld(&bar[XB_XGEN(b.x)]) == gen, bar);
;             __builtin_amdgcn_fence(__ATOMIC_ACQUIRE, "agent");
;             asm volatile("s_waitcnt vmcnt(0)" ::: "memory");
;         }
;     }
;     __syncthreads();
; }
.Lseam_ret:
	s_cmp_eq_u32 s99, 1
	s_cbranch_scc1 .Lseam1_ret
	s_cmp_eq_u32 s99, 5
	s_cbranch_scc1 .LBB0_588
	s_cmp_eq_u32 s99, 6
	s_cbranch_scc1 .LBB0_749
	s_cmp_eq_u32 s99, 7
	s_cbranch_scc1 .LBB0_78
